# v54 + attention loop: static s_setprio 1 for waves 0-3 during each stream pass
# speedup vs baseline: 1.0005x; 1.0005x over previous
.Lat_noqk1_2:
	s_mov_b32 s5, 1
	s_mov_b32 s12, 16384
	s_mov_b32 s84, 32768
	v_add_u32_e32 v215, s84, v161
	v_add_u32_e32 v165, s84, v162
	v_add_u32_e32 v216, s84, v163
	v_add_u32_e32 v217, s84, v164
	ds_read_b64_tr_b16 v[224:225], v215 offset:0
	ds_read_b64_tr_b16 v[226:227], v215 offset:2048
	ds_read_b64_tr_b16 v[228:229], v165 offset:0
	ds_read_b64_tr_b16 v[230:231], v165 offset:2048
	ds_read_b64_tr_b16 v[232:233], v216 offset:0
	ds_read_b64_tr_b16 v[234:235], v216 offset:2048
	ds_read_b64_tr_b16 v[236:237], v217 offset:0
	ds_read_b64_tr_b16 v[238:239], v217 offset:2048
	ds_read_b64_tr_b16 v[240:241], v215 offset:4096
	ds_read_b64_tr_b16 v[242:243], v215 offset:6144
	ds_read_b64_tr_b16 v[130:131], v165 offset:4096
	ds_read_b64_tr_b16 v[132:133], v165 offset:6144
	ds_read_b64_tr_b16 v[134:135], v216 offset:4096
	ds_read_b64_tr_b16 v[136:137], v216 offset:6144
	ds_read_b64_tr_b16 v[184:185], v217 offset:4096
	ds_read_b64_tr_b16 v[186:187], v217 offset:6144
	s_waitcnt vmcnt(3) lgkmcnt(15)
	s_barrier
	s_cmp_lt_u32 s68, 0x1000
	s_cbranch_scc0 .Lat_np
	s_setprio 1
.Lat_np:
.Lat_loop:
	v_add_u32_e32 v188, s12, v157
	v_add_u32_e32 v189, s12, v158
	v_add_u32_e32 v222, s12, v159
	v_add_u32_e32 v223, s12, v160
	s_cmp_ge_i32 s5, s81
	s_cbranch_scc1 .Lat_rare_8
	s_waitcnt lgkmcnt(8)
	v_mfma_f32_32x32x16_bf16 v[0:15], v[224:227], v[114:117], v[0:15]
	v_exp_f32_e32 v82, v82
	v_exp_f32_e32 v83, v83
	ds_read_b64_tr_b16 v[224:225], v215 offset:8192
	ds_read_b64_tr_b16 v[226:227], v215 offset:10240
	v_mfma_f32_32x32x16_bf16 v[16:31], v[228:231], v[114:117], v[16:31]
	v_exp_f32_e32 v84, v84
	v_exp_f32_e32 v85, v85
	v_add_f32_e32 v180, v82, v83
	ds_read_b64_tr_b16 v[228:229], v165 offset:8192
	ds_read_b64_tr_b16 v[230:231], v165 offset:10240
	v_mfma_f32_32x32x16_bf16 v[32:47], v[232:235], v[114:117], v[32:47]
	v_exp_f32_e32 v86, v86
	v_exp_f32_e32 v87, v87
	v_add_f32_e32 v180, v180, v84
	v_add_f32_e32 v180, v180, v85
	ds_read_b64_tr_b16 v[232:233], v216 offset:8192
	ds_read_b64_tr_b16 v[234:235], v216 offset:10240
	v_mfma_f32_32x32x16_bf16 v[48:63], v[236:239], v[114:117], v[48:63]
	v_exp_f32_e32 v88, v88
	v_exp_f32_e32 v89, v89
	v_add_f32_e32 v180, v180, v86
	v_add_f32_e32 v180, v180, v87
	ds_read_b64_tr_b16 v[236:237], v217 offset:8192
	ds_read_b64_tr_b16 v[238:239], v217 offset:10240
	s_waitcnt lgkmcnt(8)
	v_mfma_f32_32x32x16_bf16 v[0:15], v[240:243], v[118:121], v[0:15]
	v_exp_f32_e32 v90, v90
	v_exp_f32_e32 v91, v91
	v_add_f32_e32 v180, v180, v88
	v_cvt_pk_bf16_f32 v114, v82, v83
	ds_read_b64_tr_b16 v[240:241], v215 offset:12288
	ds_read_b64_tr_b16 v[242:243], v215 offset:14336
	v_mfma_f32_32x32x16_bf16 v[16:31], v[130:133], v[118:121], v[16:31]
	v_exp_f32_e32 v92, v92
	v_exp_f32_e32 v93, v93
	v_add_f32_e32 v180, v180, v89
	v_cvt_pk_bf16_f32 v115, v84, v85
	ds_read_b64_tr_b16 v[130:131], v165 offset:12288
	ds_read_b64_tr_b16 v[132:133], v165 offset:14336
	v_mfma_f32_32x32x16_bf16 v[32:47], v[134:137], v[118:121], v[32:47]
	v_exp_f32_e32 v94, v94
	v_exp_f32_e32 v95, v95
	v_add_f32_e32 v180, v180, v90
	v_cvt_pk_bf16_f32 v116, v86, v87
	ds_read_b64_tr_b16 v[134:135], v216 offset:12288
	ds_read_b64_tr_b16 v[136:137], v216 offset:14336
	v_mfma_f32_32x32x16_bf16 v[48:63], v[184:187], v[118:121], v[48:63]
	v_exp_f32_e32 v96, v96
	v_exp_f32_e32 v97, v97
	v_add_f32_e32 v180, v180, v91
	v_cvt_pk_bf16_f32 v117, v88, v89
	ds_read_b64_tr_b16 v[184:185], v217 offset:12288
	ds_read_b64_tr_b16 v[186:187], v217 offset:14336
	s_waitcnt lgkmcnt(8)
	v_mfma_f32_32x32x16_bf16 v[0:15], v[224:227], v[122:125], v[0:15]
	v_exp_f32_e32 v98, v98
	v_exp_f32_e32 v99, v99
	v_add_f32_e32 v180, v180, v92
	v_cvt_pk_bf16_f32 v118, v90, v91
	v_mfma_f32_32x32x16_bf16 v[16:31], v[228:231], v[122:125], v[16:31]
	v_exp_f32_e32 v100, v100
	v_exp_f32_e32 v101, v101
	v_add_f32_e32 v180, v180, v93
	v_cvt_pk_bf16_f32 v119, v92, v93
	v_mfma_f32_32x32x16_bf16 v[32:47], v[232:235], v[122:125], v[32:47]
	v_exp_f32_e32 v102, v102
	v_exp_f32_e32 v103, v103
	v_add_f32_e32 v180, v180, v94
	v_cvt_pk_bf16_f32 v120, v94, v95
	v_mfma_f32_32x32x16_bf16 v[48:63], v[236:239], v[122:125], v[48:63]
	v_exp_f32_e32 v104, v104
	v_exp_f32_e32 v105, v105
	v_add_f32_e32 v180, v180, v95
	v_cvt_pk_bf16_f32 v121, v96, v97
	ds_read_b128 v[224:227], v188
	ds_read_b128 v[228:231], v189
	ds_read_b128 v[232:235], v222
	ds_read_b128 v[236:239], v223
	s_waitcnt lgkmcnt(4)
	v_mfma_f32_32x32x16_bf16 v[0:15], v[240:243], v[126:129], v[0:15]
	v_exp_f32_e32 v106, v106
	v_exp_f32_e32 v107, v107
	v_add_f32_e32 v180, v180, v96
	v_add_f32_e32 v180, v180, v97
	v_mfma_f32_32x32x16_bf16 v[16:31], v[130:133], v[126:129], v[16:31]
	v_exp_f32_e32 v108, v108
	v_exp_f32_e32 v109, v109
	v_add_f32_e32 v180, v180, v98
	v_add_f32_e32 v180, v180, v99
	v_mfma_f32_32x32x16_bf16 v[32:47], v[134:137], v[126:129], v[32:47]
	v_exp_f32_e32 v110, v110
	v_exp_f32_e32 v111, v111
	v_add_f32_e32 v180, v180, v100
	v_add_f32_e32 v180, v180, v101
	v_mfma_f32_32x32x16_bf16 v[48:63], v[184:187], v[126:129], v[48:63]
	v_exp_f32_e32 v112, v112
	v_exp_f32_e32 v113, v113
	v_add_f32_e32 v180, v180, v102
	v_add_f32_e32 v180, v180, v103
	ds_read_b128 v[240:243], v188 offset:4096
	ds_read_b128 v[130:133], v189 offset:4096
	ds_read_b128 v[134:137], v222 offset:4096
	ds_read_b128 v[184:187], v223 offset:4096
	s_waitcnt lgkmcnt(4)
	v_mfma_f32_32x32x16_bf16 v[82:97], v[224:227], v[150:153], v[64:79]
	v_add_f32_e32 v180, v180, v104
	v_add_f32_e32 v180, v180, v105
	v_add_f32_e32 v180, v180, v106
	v_cvt_pk_bf16_f32 v122, v98, v99
	v_cvt_pk_bf16_f32 v123, v100, v101
	s_add_i32 m0, s13, s68
	s_nop 0
	global_load_lds_dwordx4 v154, s[14:15]
	v_mfma_f32_32x32x16_bf16 v[82:97], v[228:231], v[146:149], v[82:97]
	v_add_f32_e32 v180, v180, v107
	v_add_f32_e32 v180, v180, v108
	v_add_f32_e32 v180, v180, v109
	v_cvt_pk_bf16_f32 v124, v102, v103
	v_cvt_pk_bf16_f32 v125, v104, v105
	s_add_i32 m0, s17, s69
	s_nop 0
	global_load_lds_dwordx4 v155, s[18:19]
	v_mfma_f32_32x32x16_bf16 v[82:97], v[232:235], v[142:145], v[82:97]
	v_add_f32_e32 v180, v180, v110
	v_add_f32_e32 v180, v180, v111
	v_cvt_pk_bf16_f32 v126, v106, v107
	v_cvt_pk_bf16_f32 v127, v108, v109
	s_add_i32 m0, m0, 0x400
	s_nop 0
	global_load_lds_dwordx4 v156, s[18:19]
	v_mfma_f32_32x32x16_bf16 v[82:97], v[236:239], v[138:141], v[82:97]
	v_add_f32_e32 v180, v180, v112
	v_add_f32_e32 v180, v180, v113
	v_cvt_pk_bf16_f32 v128, v110, v111
	v_cvt_pk_bf16_f32 v129, v112, v113
	v_cmp_ngt_f32_e32 vcc, s23, v180
	s_add_i32 s12, s12, 8192
	s_cmp_eq_u32 s12, 32768
	s_cselect_b32 s12, 0, s12
	s_add_i32 s84, s84, 16384
	s_cmp_eq_u32 s84, 114688
	s_cselect_b32 s84, 32768, s84
	s_waitcnt lgkmcnt(0)
	v_mfma_f32_32x32x16_bf16 v[98:113], v[240:243], v[150:153], v[64:79]
	v_add_u32_e32 v215, s84, v161
	v_add_u32_e32 v165, s84, v162
	v_add_u32_e32 v216, s84, v163
	v_add_u32_e32 v217, s84, v164
	ds_read_b64_tr_b16 v[224:225], v215 offset:0
	ds_read_b64_tr_b16 v[226:227], v215 offset:2048
	s_add_i32 s13, s13, 8192
	s_cmp_eq_u32 s13, 32768
	s_cselect_b32 s13, 0, s13
	v_mfma_f32_32x32x16_bf16 v[98:113], v[130:133], v[146:149], v[98:113]
	ds_read_b64_tr_b16 v[228:229], v165 offset:0
	ds_read_b64_tr_b16 v[230:231], v165 offset:2048
	ds_read_b64_tr_b16 v[232:233], v216 offset:0
	ds_read_b64_tr_b16 v[234:235], v216 offset:2048
	s_add_i32 s17, s17, 16384
	s_cmp_eq_u32 s17, 114688
	s_cselect_b32 s17, 32768, s17
	v_mfma_f32_32x32x16_bf16 v[98:113], v[134:137], v[142:145], v[98:113]
	ds_read_b64_tr_b16 v[236:237], v217 offset:0
	ds_read_b64_tr_b16 v[238:239], v217 offset:2048
	s_add_i32 s85, s85, 1
	s_cmp_lt_u32 s85, s6
	s_cselect_b32 s8, 0x40000, 0
	v_mfma_f32_32x32x16_bf16 v[98:113], v[184:187], v[138:141], v[98:113]
	s_add_u32 s14, s14, s8
	s_addc_u32 s15, s15, 0
	s_add_u32 s18, s18, s8
	s_addc_u32 s19, s19, 0
	ds_read_b64_tr_b16 v[240:241], v215 offset:4096
	ds_read_b64_tr_b16 v[242:243], v215 offset:6144
	ds_read_b64_tr_b16 v[130:131], v165 offset:4096
	ds_read_b64_tr_b16 v[132:133], v165 offset:6144
	ds_read_b64_tr_b16 v[134:135], v216 offset:4096
	ds_read_b64_tr_b16 v[136:137], v216 offset:6144
	ds_read_b64_tr_b16 v[184:185], v217 offset:4096
	ds_read_b64_tr_b16 v[186:187], v217 offset:6144
	s_cbranch_vccz .Lat_norescale_9
	ds_bpermute_b32 v182, v214, v180
	s_waitcnt lgkmcnt(0)
	v_add_f32_e32 v182, v180, v182
	v_min_f32_e32 v182, 0x7f61b1e6, v182
	v_log_f32_e32 v182, v182
	s_nop 0
	v_floor_f32_e32 v182, v182
	v_max_f32_e32 v182, 0, v182
	v_exp_f32_e64 v183, -v182
	v_add_f32_e32 v80, v80, v182
	v_mul_f32_e32 v81, v81, v183
	v_mul_f32_e32 v180, v180, v183
	v_xor_b32_e32 v64, 0x80000000, v80
	v_mov_b32_e32 v65, v64
	v_mov_b32_e32 v66, v64
	v_mov_b32_e32 v67, v64
	v_mov_b32_e32 v68, v64
	v_mov_b32_e32 v69, v64
	v_mov_b32_e32 v70, v64
	v_mov_b32_e32 v71, v64
	v_mov_b32_e32 v72, v64
	v_mov_b32_e32 v73, v64
	v_mov_b32_e32 v74, v64
	v_mov_b32_e32 v75, v64
	v_mov_b32_e32 v76, v64
	v_mov_b32_e32 v77, v64
	v_mov_b32_e32 v78, v64
	v_mov_b32_e32 v79, v64
	v_sub_f32_e32 v82, v82, v182
	v_sub_f32_e32 v83, v83, v182
	v_sub_f32_e32 v84, v84, v182
	v_sub_f32_e32 v85, v85, v182
	v_sub_f32_e32 v86, v86, v182
	v_sub_f32_e32 v87, v87, v182
	v_sub_f32_e32 v88, v88, v182
	v_sub_f32_e32 v89, v89, v182
	v_sub_f32_e32 v90, v90, v182
	v_sub_f32_e32 v91, v91, v182
	v_sub_f32_e32 v92, v92, v182
	v_sub_f32_e32 v93, v93, v182
	v_sub_f32_e32 v94, v94, v182
	v_sub_f32_e32 v95, v95, v182
	v_sub_f32_e32 v96, v96, v182
	v_sub_f32_e32 v97, v97, v182
	v_sub_f32_e32 v98, v98, v182
	v_sub_f32_e32 v99, v99, v182
	v_sub_f32_e32 v100, v100, v182
	v_sub_f32_e32 v101, v101, v182
	v_sub_f32_e32 v102, v102, v182
	v_sub_f32_e32 v103, v103, v182
	v_sub_f32_e32 v104, v104, v182
	v_sub_f32_e32 v105, v105, v182
	v_sub_f32_e32 v106, v106, v182
	v_sub_f32_e32 v107, v107, v182
	v_sub_f32_e32 v108, v108, v182
	v_sub_f32_e32 v109, v109, v182
	v_sub_f32_e32 v110, v110, v182
	v_sub_f32_e32 v111, v111, v182
	v_sub_f32_e32 v112, v112, v182
	v_sub_f32_e32 v113, v113, v182
	v_mul_f32_e32 v0, v0, v183
	v_mul_f32_e32 v1, v1, v183
	v_mul_f32_e32 v2, v2, v183
	v_mul_f32_e32 v3, v3, v183
	v_mul_f32_e32 v4, v4, v183
	v_mul_f32_e32 v5, v5, v183
	v_mul_f32_e32 v6, v6, v183
	v_mul_f32_e32 v7, v7, v183
	v_mul_f32_e32 v8, v8, v183
	v_mul_f32_e32 v9, v9, v183
	v_mul_f32_e32 v10, v10, v183
	v_mul_f32_e32 v11, v11, v183
	v_mul_f32_e32 v12, v12, v183
	v_mul_f32_e32 v13, v13, v183
	v_mul_f32_e32 v14, v14, v183
	v_mul_f32_e32 v15, v15, v183
	v_mul_f32_e32 v16, v16, v183
	v_mul_f32_e32 v17, v17, v183
	v_mul_f32_e32 v18, v18, v183
	v_mul_f32_e32 v19, v19, v183
	v_mul_f32_e32 v20, v20, v183
	v_mul_f32_e32 v21, v21, v183
	v_mul_f32_e32 v22, v22, v183
	v_mul_f32_e32 v23, v23, v183
	v_mul_f32_e32 v24, v24, v183
	v_mul_f32_e32 v25, v25, v183
	v_mul_f32_e32 v26, v26, v183
	v_mul_f32_e32 v27, v27, v183
	v_mul_f32_e32 v28, v28, v183
	v_mul_f32_e32 v29, v29, v183
	v_mul_f32_e32 v30, v30, v183
	v_mul_f32_e32 v31, v31, v183
	v_mul_f32_e32 v32, v32, v183
	v_mul_f32_e32 v33, v33, v183
	v_mul_f32_e32 v34, v34, v183
	v_mul_f32_e32 v35, v35, v183
	v_mul_f32_e32 v36, v36, v183
	v_mul_f32_e32 v37, v37, v183
	v_mul_f32_e32 v38, v38, v183
	v_mul_f32_e32 v39, v39, v183
	v_mul_f32_e32 v40, v40, v183
	v_mul_f32_e32 v41, v41, v183
	v_mul_f32_e32 v42, v42, v183
	v_mul_f32_e32 v43, v43, v183
	v_mul_f32_e32 v44, v44, v183
	v_mul_f32_e32 v45, v45, v183
	v_mul_f32_e32 v46, v46, v183
	v_mul_f32_e32 v47, v47, v183
	v_mul_f32_e32 v48, v48, v183
	v_mul_f32_e32 v49, v49, v183
	v_mul_f32_e32 v50, v50, v183
	v_mul_f32_e32 v51, v51, v183
	v_mul_f32_e32 v52, v52, v183
	v_mul_f32_e32 v53, v53, v183
	v_mul_f32_e32 v54, v54, v183
	v_mul_f32_e32 v55, v55, v183
	v_mul_f32_e32 v56, v56, v183
	v_mul_f32_e32 v57, v57, v183
	v_mul_f32_e32 v58, v58, v183
	v_mul_f32_e32 v59, v59, v183
	v_mul_f32_e32 v60, v60, v183
	v_mul_f32_e32 v61, v61, v183
	v_mul_f32_e32 v62, v62, v183
	v_mul_f32_e32 v63, v63, v183
	v_lshlrev_b32_e32 v181, 16, v114
	v_and_b32_e32 v114, 0xffff0000, v114
	v_mul_f32_e32 v181, v181, v183
	v_mul_f32_e32 v114, v114, v183
	v_cvt_pk_bf16_f32 v114, v181, v114
	v_lshlrev_b32_e32 v181, 16, v115
	v_and_b32_e32 v115, 0xffff0000, v115
	v_mul_f32_e32 v181, v181, v183
	v_mul_f32_e32 v115, v115, v183
	v_cvt_pk_bf16_f32 v115, v181, v115
	v_lshlrev_b32_e32 v181, 16, v116
	v_and_b32_e32 v116, 0xffff0000, v116
	v_mul_f32_e32 v181, v181, v183
	v_mul_f32_e32 v116, v116, v183
	v_cvt_pk_bf16_f32 v116, v181, v116
	v_lshlrev_b32_e32 v181, 16, v117
	v_and_b32_e32 v117, 0xffff0000, v117
	v_mul_f32_e32 v181, v181, v183
	v_mul_f32_e32 v117, v117, v183
	v_cvt_pk_bf16_f32 v117, v181, v117
	v_lshlrev_b32_e32 v181, 16, v118
	v_and_b32_e32 v118, 0xffff0000, v118
	v_mul_f32_e32 v181, v181, v183
	v_mul_f32_e32 v118, v118, v183
	v_cvt_pk_bf16_f32 v118, v181, v118
	v_lshlrev_b32_e32 v181, 16, v119
	v_and_b32_e32 v119, 0xffff0000, v119
	v_mul_f32_e32 v181, v181, v183
	v_mul_f32_e32 v119, v119, v183
	v_cvt_pk_bf16_f32 v119, v181, v119
	v_lshlrev_b32_e32 v181, 16, v120
	v_and_b32_e32 v120, 0xffff0000, v120
	v_mul_f32_e32 v181, v181, v183
	v_mul_f32_e32 v120, v120, v183
	v_cvt_pk_bf16_f32 v120, v181, v120
	v_lshlrev_b32_e32 v181, 16, v121
	v_and_b32_e32 v121, 0xffff0000, v121
	v_mul_f32_e32 v181, v181, v183
	v_mul_f32_e32 v121, v121, v183
	v_cvt_pk_bf16_f32 v121, v181, v121
	v_lshlrev_b32_e32 v181, 16, v122
	v_and_b32_e32 v122, 0xffff0000, v122
	v_mul_f32_e32 v181, v181, v183
	v_mul_f32_e32 v122, v122, v183
	v_cvt_pk_bf16_f32 v122, v181, v122
	v_lshlrev_b32_e32 v181, 16, v123
	v_and_b32_e32 v123, 0xffff0000, v123
	v_mul_f32_e32 v181, v181, v183
	v_mul_f32_e32 v123, v123, v183
	v_cvt_pk_bf16_f32 v123, v181, v123
	v_lshlrev_b32_e32 v181, 16, v124
	v_and_b32_e32 v124, 0xffff0000, v124
	v_mul_f32_e32 v181, v181, v183
	v_mul_f32_e32 v124, v124, v183
	v_cvt_pk_bf16_f32 v124, v181, v124
	v_lshlrev_b32_e32 v181, 16, v125
	v_and_b32_e32 v125, 0xffff0000, v125
	v_mul_f32_e32 v181, v181, v183
	v_mul_f32_e32 v125, v125, v183
	v_cvt_pk_bf16_f32 v125, v181, v125
	v_lshlrev_b32_e32 v181, 16, v126
	v_and_b32_e32 v126, 0xffff0000, v126
	v_mul_f32_e32 v181, v181, v183
	v_mul_f32_e32 v126, v126, v183
	v_cvt_pk_bf16_f32 v126, v181, v126
	v_lshlrev_b32_e32 v181, 16, v127
	v_and_b32_e32 v127, 0xffff0000, v127
	v_mul_f32_e32 v181, v181, v183
	v_mul_f32_e32 v127, v127, v183
	v_cvt_pk_bf16_f32 v127, v181, v127
	v_lshlrev_b32_e32 v181, 16, v128
	v_and_b32_e32 v128, 0xffff0000, v128
	v_mul_f32_e32 v181, v181, v183
	v_mul_f32_e32 v128, v128, v183
	v_cvt_pk_bf16_f32 v128, v181, v128
	v_lshlrev_b32_e32 v181, 16, v129
	v_and_b32_e32 v129, 0xffff0000, v129
	v_mul_f32_e32 v181, v181, v183
	v_mul_f32_e32 v129, v129, v183
	v_cvt_pk_bf16_f32 v129, v181, v129

.Lat_nolast_11:
	s_setprio 0
	s_waitcnt vmcnt(0) lgkmcnt(0)
	s_barrier
	ds_bpermute_b32 v182, v214, v81
	s_waitcnt lgkmcnt(0)
	v_add_f32_e32 v64, v81, v182
	v_div_scale_f32 v65, s[36:37], v64, v64, 1.0
	v_rcp_f32_e32 v66, v65
	v_div_scale_f32 v67, vcc, 1.0, v64, 1.0
	v_fma_f32 v68, -v65, v66, 1.0
	v_fmac_f32_e32 v66, v68, v66
	v_mul_f32_e32 v68, v67, v66
	v_fma_f32 v69, -v65, v68, v67
	v_fmac_f32_e32 v68, v69, v66
	v_fma_f32 v65, -v65, v68, v67
	v_div_fmas_f32 v65, v65, v66, v68
	v_div_fixup_f32 v72, v65, v64, 1.0
	v_mul_f32_e32 v0, v0, v72
	v_mul_f32_e32 v1, v1, v72
	v_mul_f32_e32 v2, v2, v72
	v_mul_f32_e32 v3, v3, v72
	v_mul_f32_e32 v4, v4, v72
	v_mul_f32_e32 v5, v5, v72
	v_mul_f32_e32 v6, v6, v72
	v_mul_f32_e32 v7, v7, v72
	v_mul_f32_e32 v8, v8, v72
	v_mul_f32_e32 v9, v9, v72
	v_mul_f32_e32 v10, v10, v72
	v_mul_f32_e32 v11, v11, v72
	v_mul_f32_e32 v12, v12, v72
	v_mul_f32_e32 v13, v13, v72
	v_mul_f32_e32 v14, v14, v72
	v_mul_f32_e32 v15, v15, v72
	v_mul_f32_e32 v16, v16, v72
	v_mul_f32_e32 v17, v17, v72
	v_mul_f32_e32 v18, v18, v72
	v_mul_f32_e32 v19, v19, v72
	v_mul_f32_e32 v20, v20, v72
	v_mul_f32_e32 v21, v21, v72
	v_mul_f32_e32 v22, v22, v72
	v_mul_f32_e32 v23, v23, v72
	v_mul_f32_e32 v24, v24, v72
	v_mul_f32_e32 v25, v25, v72
	v_mul_f32_e32 v26, v26, v72
	v_mul_f32_e32 v27, v27, v72
	v_mul_f32_e32 v28, v28, v72
	v_mul_f32_e32 v29, v29, v72
	v_mul_f32_e32 v30, v30, v72
	v_mul_f32_e32 v31, v31, v72
	v_mul_f32_e32 v32, v32, v72
	v_mul_f32_e32 v33, v33, v72
	v_mul_f32_e32 v34, v34, v72
	v_mul_f32_e32 v35, v35, v72
	v_mul_f32_e32 v36, v36, v72
	v_mul_f32_e32 v37, v37, v72
	v_mul_f32_e32 v38, v38, v72
	v_mul_f32_e32 v39, v39, v72
	v_mul_f32_e32 v40, v40, v72
	v_mul_f32_e32 v41, v41, v72
	v_mul_f32_e32 v42, v42, v72
	v_mul_f32_e32 v43, v43, v72
	v_mul_f32_e32 v44, v44, v72
	v_mul_f32_e32 v45, v45, v72
	v_mul_f32_e32 v46, v46, v72
	v_mul_f32_e32 v47, v47, v72
	v_mul_f32_e32 v48, v48, v72
	v_mul_f32_e32 v49, v49, v72
	v_mul_f32_e32 v50, v50, v72
	v_mul_f32_e32 v51, v51, v72
	v_mul_f32_e32 v52, v52, v72
	v_mul_f32_e32 v53, v53, v72
	v_mul_f32_e32 v54, v54, v72
	v_mul_f32_e32 v55, v55, v72
	v_mul_f32_e32 v56, v56, v72
	v_mul_f32_e32 v57, v57, v72
	v_mul_f32_e32 v58, v58, v72
	v_mul_f32_e32 v59, v59, v72
	v_mul_f32_e32 v60, v60, v72
	v_mul_f32_e32 v61, v61, v72
	v_mul_f32_e32 v62, v62, v72
	v_mul_f32_e32 v63, v63, v72
	s_cmp_lg_u32 s7, 0
	s_cbranch_scc1 .Lat_combine
	v_and_b32_e32 v82, 63, v195
	v_mul_u32_u24_e32 v82, 0xf0, v82
	v_sub_u32_e32 v82, 0, v82
	v_ashrrev_i32_e32 v83, 31, v82
	s_movk_i32 s8, 0x1000
	s_mov_b32 s9, 0
	v_lshl_add_u64 v[82:83], v[170:171], 0, v[82:83]
	v_lshl_add_u64 v[84:85], v[82:83], 0, s[8:9]
	v_lshl_add_u64 v[86:87], v[84:85], 0, s[8:9]
	v_lshl_add_u64 v[88:89], v[86:87], 0, s[8:9]
	global_store_dwordx4 v[82:83], v[0:3], off
	global_store_dwordx4 v[82:83], v[4:7], off offset:1024
	global_store_dwordx4 v[82:83], v[8:11], off offset:2048
	global_store_dwordx4 v[82:83], v[12:15], off offset:3072
	global_store_dwordx4 v[84:85], v[16:19], off
	global_store_dwordx4 v[84:85], v[20:23], off offset:1024
	global_store_dwordx4 v[84:85], v[24:27], off offset:2048
	global_store_dwordx4 v[84:85], v[28:31], off offset:3072
	global_store_dwordx4 v[86:87], v[32:35], off
	global_store_dwordx4 v[86:87], v[36:39], off offset:1024
	global_store_dwordx4 v[86:87], v[40:43], off offset:2048
	global_store_dwordx4 v[86:87], v[44:47], off offset:3072
	global_store_dwordx4 v[88:89], v[48:51], off
	global_store_dwordx4 v[88:89], v[52:55], off offset:1024
	global_store_dwordx4 v[88:89], v[56:59], off offset:2048
	global_store_dwordx4 v[88:89], v[60:63], off offset:3072
	s_mov_b32 s7, 1
	s_branch .Lat_stream
